# QK-norm phase wave sums: the xor-16 ds_swizzle step replaced by v_permlane16_swap (no LDS round trip left in the butterfly)
# speedup vs baseline: 1.0064x; 1.0004x over previous
; __device__ __forceinline__ float bf_lo(unsigned w) { return __uint_as_float(w << 16); }
; __device__ __forceinline__ float bf_hi(unsigned w) { return __uint_as_float(w & 0xffff0000u); }
; __device__ __forceinline__ unsigned pk2(float lo, float hi) { return f2bf(lo) | (f2bf(hi) << 16); }
; #define WS_SWZ(x, pat) __int_as_float(__builtin_amdgcn_ds_swizzle(__float_as_int(x), (pat)))
; __device__ __forceinline__ float wave_sum(float v) {
;     ...
;     v += WS_SWZ(v, 0x041F); v += WS_SWZ(v, 0x081F); v += WS_SWZ(v, 0x101F); v += WS_SWZ(v, 0x201F); v += WS_SWZ(v, 0x401F);
;     ...
;     auto rr = __builtin_amdgcn_permlane32_swap(__float_as_uint(v), __float_as_uint(v), false, false);
;     return __uint_as_float(rr[0]) + __uint_as_float(rr[1]);
; }
; __global__ void __launch_bounds__(NWAVES * 64) fwd_kernel(Args args) {
;     ...
;                 bf16_t* base = QKV + (size_t)r * NIN;
;                 unsigned wv[10];
; #pragma unroll
;                 for (int hh = 0; hh < 10; ++hh) wv[hh] = *((const unsigned*)(base + (hh < 8 ? 3072 + hh * 128 : 4096 + (hh - 8) * 128)) + lane);
;                 const float gq0 = qkg[2 * lane], gq1 = qkg[2 * lane + 1], gk0 = qkg[128 + 2 * lane], gk1 = qkg[128 + 2 * lane + 1];
; #pragma unroll
;                 for (int hh = 0; hh < 10; ++hh) { const int off = hh < 8 ? 3072 + hh * 128 : 4096 + (hh - 8) * 128; const float qs = hh < 8 ? QSCALE_B : 1.f;
;                     const float x0 = pg8::bf_lo(wv[hh]), x1 = pg8::bf_hi(wv[hh]);
;                     const float s2 = wave_sum(x0 * x0 + x1 * x1); const float rn = __builtin_amdgcn_rsqf(s2 * (1.0f / 128.0f) + EPS);
;                     const float y0 = x0 * rn * (hh < 8 ? gq0 : gk0), y1 = x1 * rn * (hh < 8 ? gq1 : gk1);
;                     *((unsigned*)(base + off) + lane) = pk2((y0 * c - y1 * sn) * qs, (y0 * sn + y1 * c) * qs); }
.LBB0_414:
	flat_load_dword v17, v[6:7]
	flat_load_dword v18, v[6:7] offset:256
	flat_load_dword v19, v[6:7] offset:512
	flat_load_dword v16, v[6:7] offset:768
	flat_load_dword v15, v[6:7] offset:1024
	flat_load_dword v14, v[6:7] offset:1280
	flat_load_dword v13, v[6:7] offset:1536
	flat_load_dword v12, v[6:7] offset:1792
	flat_load_dword v11, v[6:7] offset:2048
	flat_load_dword v10, v[6:7] offset:2304
	s_add_i32 s4, s4, s47
	s_cmpk_gt_i32 s4, 0x604f
	s_waitcnt vmcnt(0) lgkmcnt(0)
	v_lshlrev_b32_e32 v20, 16, v17
	v_and_b32_e32 v17, 0xffff0000, v17
	v_mul_f32_e32 v21, v17, v17
	v_fmac_f32_e32 v21, v20, v20
	s_nop 1
	v_add_f32_dpp v21, v21, v21 quad_perm:[1,0,3,2] row_mask:0xf bank_mask:0xf
	s_nop 1
	v_add_f32_dpp v21, v21, v21 quad_perm:[2,3,0,1] row_mask:0xf bank_mask:0xf
	s_nop 1
	v_add_f32_dpp v21, v21, v21 row_half_mirror row_mask:0xf bank_mask:0xf
	s_nop 1
	v_add_f32_dpp v21, v21, v21 row_mirror row_mask:0xf bank_mask:0xf
	v_mov_b32_e32 v22, v21
	s_nop 1
	v_permlane16_swap_b32_e32 v21, v22
	s_waitcnt lgkmcnt(0)
	v_add_f32_e32 v21, v21, v22
	v_mov_b32_e32 v22, v21
	s_nop 1
	v_permlane32_swap_b32_e32 v21, v22
	v_add_f32_e32 v21, v21, v22
	v_fmamk_f32 v21, v21, 0x3c000000, v215
	v_rsq_f32_e32 v21, v21
	s_nop 0
	v_mul_f32_e32 v17, v21, v17
	v_mul_f32_e32 v20, v21, v20
	v_mul_f32_e32 v17, v3, v17
	v_mul_f32_e32 v20, v2, v20
	v_mul_f32_e32 v21, v0, v17
	v_fma_f32 v21, v9, v20, -v21
	v_mul_f32_e32 v17, v9, v17
	v_mul_f32_e32 v21, 0x3e0293ee, v21
	v_fmac_f32_e32 v17, v0, v20
	v_mul_f32_e32 v17, 0x3e0293ee, v17
	v_bfe_u32 v20, v21, 16, 1
	v_add3_u32 v20, v21, v20, s31
	v_bfe_u32 v21, v17, 16, 1
	v_lshrrev_b32_e32 v20, 16, v20
	v_add3_u32 v17, v17, v21, s31
	v_and_or_b32 v17, v17, s71, v20
	flat_store_dword v[6:7], v17
	v_lshlrev_b32_e32 v17, 16, v18
	v_and_b32_e32 v18, 0xffff0000, v18
	v_mul_f32_e32 v20, v18, v18
	v_fmac_f32_e32 v20, v17, v17
	s_nop 1
	v_add_f32_dpp v20, v20, v20 quad_perm:[1,0,3,2] row_mask:0xf bank_mask:0xf
	s_nop 1
	v_add_f32_dpp v20, v20, v20 quad_perm:[2,3,0,1] row_mask:0xf bank_mask:0xf
	s_nop 1
	v_add_f32_dpp v20, v20, v20 row_half_mirror row_mask:0xf bank_mask:0xf
	s_nop 1
	v_add_f32_dpp v20, v20, v20 row_mirror row_mask:0xf bank_mask:0xf
	v_mov_b32_e32 v21, v20
	s_nop 1
	v_permlane16_swap_b32_e32 v20, v21
	s_waitcnt lgkmcnt(0)
	v_add_f32_e32 v20, v20, v21
	v_mov_b32_e32 v21, v20
	s_nop 1
	v_permlane32_swap_b32_e32 v20, v21
	v_add_f32_e32 v20, v20, v21
	v_fmamk_f32 v20, v20, 0x3c000000, v215
	v_rsq_f32_e32 v20, v20
	s_nop 0
	v_mul_f32_e32 v18, v20, v18
	v_mul_f32_e32 v17, v20, v17
	v_mul_f32_e32 v18, v3, v18
	v_mul_f32_e32 v17, v2, v17
	v_mul_f32_e32 v20, v0, v18
	v_fma_f32 v20, v9, v17, -v20
	v_mul_f32_e32 v18, v9, v18
	v_mul_f32_e32 v20, 0x3e0293ee, v20
	v_fmac_f32_e32 v18, v0, v17
	v_mul_f32_e32 v17, 0x3e0293ee, v18
	v_bfe_u32 v18, v20, 16, 1
	v_add3_u32 v18, v20, v18, s31
	v_bfe_u32 v20, v17, 16, 1
	v_lshrrev_b32_e32 v18, 16, v18
	v_add3_u32 v17, v17, v20, s31
	v_and_or_b32 v17, v17, s71, v18
	v_and_b32_e32 v18, 0xffff0000, v19
	flat_store_dword v[6:7], v17 offset:256
	v_lshlrev_b32_e32 v17, 16, v19
	v_mul_f32_e32 v19, v18, v18
	v_fmac_f32_e32 v19, v17, v17
	s_nop 1
	v_add_f32_dpp v19, v19, v19 quad_perm:[1,0,3,2] row_mask:0xf bank_mask:0xf
	s_nop 1
	v_add_f32_dpp v19, v19, v19 quad_perm:[2,3,0,1] row_mask:0xf bank_mask:0xf
	s_nop 1
	v_add_f32_dpp v19, v19, v19 row_half_mirror row_mask:0xf bank_mask:0xf
	s_nop 1
	v_add_f32_dpp v19, v19, v19 row_mirror row_mask:0xf bank_mask:0xf
	v_mov_b32_e32 v20, v19
	s_nop 1
	v_permlane16_swap_b32_e32 v19, v20
	s_waitcnt lgkmcnt(0)
	v_add_f32_e32 v19, v19, v20
	v_mov_b32_e32 v20, v19
	s_nop 1
	v_permlane32_swap_b32_e32 v19, v20
	v_add_f32_e32 v19, v19, v20
	v_fmamk_f32 v19, v19, 0x3c000000, v215
	v_rsq_f32_e32 v19, v19
	s_nop 0
	v_mul_f32_e32 v18, v19, v18
	v_mul_f32_e32 v17, v19, v17
	v_mul_f32_e32 v18, v3, v18
	v_mul_f32_e32 v17, v2, v17
	v_mul_f32_e32 v19, v0, v18
	v_fma_f32 v19, v9, v17, -v19
	v_mul_f32_e32 v18, v9, v18
	v_mul_f32_e32 v19, 0x3e0293ee, v19
	v_fmac_f32_e32 v18, v0, v17
	v_mul_f32_e32 v17, 0x3e0293ee, v18
	v_bfe_u32 v18, v19, 16, 1
	v_add3_u32 v18, v19, v18, s31
	v_bfe_u32 v19, v17, 16, 1
	v_lshrrev_b32_e32 v18, 16, v18
	v_add3_u32 v17, v17, v19, s31
	v_and_or_b32 v17, v17, s71, v18
	flat_store_dword v[6:7], v17 offset:512
	v_lshlrev_b32_e32 v17, 16, v16
	v_and_b32_e32 v16, 0xffff0000, v16
	v_mul_f32_e32 v18, v16, v16
	v_fmac_f32_e32 v18, v17, v17
	s_nop 1
	v_add_f32_dpp v18, v18, v18 quad_perm:[1,0,3,2] row_mask:0xf bank_mask:0xf
	s_nop 1
	v_add_f32_dpp v18, v18, v18 quad_perm:[2,3,0,1] row_mask:0xf bank_mask:0xf
	s_nop 1
	v_add_f32_dpp v18, v18, v18 row_half_mirror row_mask:0xf bank_mask:0xf
	s_nop 1
	v_add_f32_dpp v18, v18, v18 row_mirror row_mask:0xf bank_mask:0xf
	v_mov_b32_e32 v19, v18
	s_nop 1
	v_permlane16_swap_b32_e32 v18, v19
	s_waitcnt lgkmcnt(0)
	v_add_f32_e32 v18, v18, v19
	v_mov_b32_e32 v19, v18
	s_nop 1
	v_permlane32_swap_b32_e32 v18, v19
	v_add_f32_e32 v18, v18, v19
	v_fmamk_f32 v18, v18, 0x3c000000, v215
	v_rsq_f32_e32 v18, v18
	s_nop 0
	v_mul_f32_e32 v16, v18, v16
	v_mul_f32_e32 v17, v18, v17
	v_mul_f32_e32 v16, v3, v16
	v_mul_f32_e32 v17, v2, v17
	v_mul_f32_e32 v18, v0, v16
	v_fma_f32 v18, v9, v17, -v18
	v_mul_f32_e32 v16, v9, v16
	v_mul_f32_e32 v18, 0x3e0293ee, v18
	v_fmac_f32_e32 v16, v0, v17
	v_mul_f32_e32 v16, 0x3e0293ee, v16
	v_bfe_u32 v17, v18, 16, 1
	v_add3_u32 v17, v18, v17, s31
	v_bfe_u32 v18, v16, 16, 1
	v_lshrrev_b32_e32 v17, 16, v17
	v_add3_u32 v16, v16, v18, s31
	v_and_or_b32 v16, v16, s71, v17
	flat_store_dword v[6:7], v16 offset:768
	v_lshlrev_b32_e32 v16, 16, v15
	v_and_b32_e32 v15, 0xffff0000, v15
	v_mul_f32_e32 v17, v15, v15
	v_fmac_f32_e32 v17, v16, v16
	s_nop 1
	v_add_f32_dpp v17, v17, v17 quad_perm:[1,0,3,2] row_mask:0xf bank_mask:0xf
	s_nop 1
	v_add_f32_dpp v17, v17, v17 quad_perm:[2,3,0,1] row_mask:0xf bank_mask:0xf
	s_nop 1
	v_add_f32_dpp v17, v17, v17 row_half_mirror row_mask:0xf bank_mask:0xf
	s_nop 1
	v_add_f32_dpp v17, v17, v17 row_mirror row_mask:0xf bank_mask:0xf
	v_mov_b32_e32 v18, v17
	s_nop 1
	v_permlane16_swap_b32_e32 v17, v18
	s_waitcnt lgkmcnt(0)
; __device__ __forceinline__ float bf_lo(unsigned w) { return __uint_as_float(w << 16); }
; __device__ __forceinline__ float bf_hi(unsigned w) { return __uint_as_float(w & 0xffff0000u); }
; __device__ __forceinline__ unsigned pk2(float lo, float hi) { return f2bf(lo) | (f2bf(hi) << 16); }
; #define WS_SWZ(x, pat) __int_as_float(__builtin_amdgcn_ds_swizzle(__float_as_int(x), (pat)))
; __device__ __forceinline__ float wave_sum(float v) {
;     ...
;     v += WS_SWZ(v, 0x041F); v += WS_SWZ(v, 0x081F); v += WS_SWZ(v, 0x101F); v += WS_SWZ(v, 0x201F); v += WS_SWZ(v, 0x401F);
;     ...
;     auto rr = __builtin_amdgcn_permlane32_swap(__float_as_uint(v), __float_as_uint(v), false, false);
;     return __uint_as_float(rr[0]) + __uint_as_float(rr[1]);
; }
; __global__ void __launch_bounds__(NWAVES * 64) fwd_kernel(Args args) {
;     ...
;                 bf16_t* base = QKV + (size_t)r * NIN;
;                 unsigned wv[10];
; #pragma unroll
;                 for (int hh = 0; hh < 10; ++hh) wv[hh] = *((const unsigned*)(base + (hh < 8 ? 3072 + hh * 128 : 4096 + (hh - 8) * 128)) + lane);
;                 const float gq0 = qkg[2 * lane], gq1 = qkg[2 * lane + 1], gk0 = qkg[128 + 2 * lane], gk1 = qkg[128 + 2 * lane + 1];
; #pragma unroll
;                 for (int hh = 0; hh < 10; ++hh) { const int off = hh < 8 ? 3072 + hh * 128 : 4096 + (hh - 8) * 128; const float qs = hh < 8 ? QSCALE_B : 1.f;
;                     const float x0 = pg8::bf_lo(wv[hh]), x1 = pg8::bf_hi(wv[hh]);
;                     const float s2 = wave_sum(x0 * x0 + x1 * x1); const float rn = __builtin_amdgcn_rsqf(s2 * (1.0f / 128.0f) + EPS);
;                     const float y0 = x0 * rn * (hh < 8 ? gq0 : gk0), y1 = x1 * rn * (hh < 8 ? gq1 : gk1);
;                     *((unsigned*)(base + off) + lane) = pk2((y0 * c - y1 * sn) * qs, (y0 * sn + y1 * c) * qs); }
	v_add_f32_e32 v17, v17, v18
	v_mov_b32_e32 v18, v17
	s_nop 1
	v_permlane32_swap_b32_e32 v17, v18
	v_add_f32_e32 v17, v17, v18
	v_fmamk_f32 v17, v17, 0x3c000000, v215
	v_rsq_f32_e32 v17, v17
	s_nop 0
	v_mul_f32_e32 v15, v17, v15
	v_mul_f32_e32 v16, v17, v16
	v_mul_f32_e32 v15, v3, v15
	v_mul_f32_e32 v16, v2, v16
	v_mul_f32_e32 v17, v0, v15
	v_fma_f32 v17, v9, v16, -v17
	v_mul_f32_e32 v15, v9, v15
	v_mul_f32_e32 v17, 0x3e0293ee, v17
	v_fmac_f32_e32 v15, v0, v16
	v_mul_f32_e32 v15, 0x3e0293ee, v15
	v_bfe_u32 v16, v17, 16, 1
	v_add3_u32 v16, v17, v16, s31
	v_bfe_u32 v17, v15, 16, 1
	v_lshrrev_b32_e32 v16, 16, v16
	v_add3_u32 v15, v15, v17, s31
	v_and_or_b32 v15, v15, s71, v16
	flat_store_dword v[6:7], v15 offset:1024
	v_lshlrev_b32_e32 v15, 16, v14
	v_and_b32_e32 v14, 0xffff0000, v14
	v_mul_f32_e32 v16, v14, v14
	v_fmac_f32_e32 v16, v15, v15
	s_nop 1
	v_add_f32_dpp v16, v16, v16 quad_perm:[1,0,3,2] row_mask:0xf bank_mask:0xf
	s_nop 1
	v_add_f32_dpp v16, v16, v16 quad_perm:[2,3,0,1] row_mask:0xf bank_mask:0xf
	s_nop 1
	v_add_f32_dpp v16, v16, v16 row_half_mirror row_mask:0xf bank_mask:0xf
	s_nop 1
	v_add_f32_dpp v16, v16, v16 row_mirror row_mask:0xf bank_mask:0xf
	v_mov_b32_e32 v17, v16
	s_nop 1
	v_permlane16_swap_b32_e32 v16, v17
	s_waitcnt lgkmcnt(0)
	v_add_f32_e32 v16, v16, v17
	v_mov_b32_e32 v17, v16
	s_nop 1
	v_permlane32_swap_b32_e32 v16, v17
	v_add_f32_e32 v16, v16, v17
	v_fmamk_f32 v16, v16, 0x3c000000, v215
	v_rsq_f32_e32 v16, v16
	s_nop 0
	v_mul_f32_e32 v14, v16, v14
	v_mul_f32_e32 v15, v16, v15
	v_mul_f32_e32 v14, v3, v14
	v_mul_f32_e32 v15, v2, v15
	v_mul_f32_e32 v16, v0, v14
	v_fma_f32 v16, v9, v15, -v16
	v_mul_f32_e32 v14, v9, v14
	v_mul_f32_e32 v16, 0x3e0293ee, v16
	v_fmac_f32_e32 v14, v0, v15
	v_mul_f32_e32 v14, 0x3e0293ee, v14
	v_bfe_u32 v15, v16, 16, 1
	v_add3_u32 v15, v16, v15, s31
	v_bfe_u32 v16, v14, 16, 1
	v_lshrrev_b32_e32 v15, 16, v15
	v_add3_u32 v14, v14, v16, s31
	v_and_or_b32 v14, v14, s71, v15
	flat_store_dword v[6:7], v14 offset:1280
	v_lshlrev_b32_e32 v14, 16, v13
	v_and_b32_e32 v13, 0xffff0000, v13
	v_mul_f32_e32 v15, v13, v13
	v_fmac_f32_e32 v15, v14, v14
	s_nop 1
	v_add_f32_dpp v15, v15, v15 quad_perm:[1,0,3,2] row_mask:0xf bank_mask:0xf
	s_nop 1
	v_add_f32_dpp v15, v15, v15 quad_perm:[2,3,0,1] row_mask:0xf bank_mask:0xf
	s_nop 1
	v_add_f32_dpp v15, v15, v15 row_half_mirror row_mask:0xf bank_mask:0xf
	s_nop 1
	v_add_f32_dpp v15, v15, v15 row_mirror row_mask:0xf bank_mask:0xf
	v_mov_b32_e32 v16, v15
	s_nop 1
	v_permlane16_swap_b32_e32 v15, v16
	s_waitcnt lgkmcnt(0)
	v_add_f32_e32 v15, v15, v16
	v_mov_b32_e32 v16, v15
	s_nop 1
	v_permlane32_swap_b32_e32 v15, v16
	v_add_f32_e32 v15, v15, v16
	v_fmamk_f32 v15, v15, 0x3c000000, v215
	v_rsq_f32_e32 v15, v15
	s_nop 0
	v_mul_f32_e32 v13, v15, v13
	v_mul_f32_e32 v14, v15, v14
	v_mul_f32_e32 v13, v3, v13
	v_mul_f32_e32 v14, v2, v14
	v_mul_f32_e32 v15, v0, v13
	v_fma_f32 v15, v9, v14, -v15
	v_mul_f32_e32 v13, v9, v13
	v_mul_f32_e32 v15, 0x3e0293ee, v15
	v_fmac_f32_e32 v13, v0, v14
	v_mul_f32_e32 v13, 0x3e0293ee, v13
	v_bfe_u32 v14, v15, 16, 1
	v_add3_u32 v14, v15, v14, s31
	v_bfe_u32 v15, v13, 16, 1
	v_lshrrev_b32_e32 v14, 16, v14
	v_add3_u32 v13, v13, v15, s31
	v_and_or_b32 v13, v13, s71, v14
	flat_store_dword v[6:7], v13 offset:1536
	v_lshlrev_b32_e32 v13, 16, v12
	v_and_b32_e32 v12, 0xffff0000, v12
	v_mul_f32_e32 v14, v12, v12
	v_fmac_f32_e32 v14, v13, v13
	s_nop 1
	v_add_f32_dpp v14, v14, v14 quad_perm:[1,0,3,2] row_mask:0xf bank_mask:0xf
	s_nop 1
	v_add_f32_dpp v14, v14, v14 quad_perm:[2,3,0,1] row_mask:0xf bank_mask:0xf
	s_nop 1
	v_add_f32_dpp v14, v14, v14 row_half_mirror row_mask:0xf bank_mask:0xf
	s_nop 1
	v_add_f32_dpp v14, v14, v14 row_mirror row_mask:0xf bank_mask:0xf
	v_mov_b32_e32 v15, v14
	s_nop 1
	v_permlane16_swap_b32_e32 v14, v15
	s_waitcnt lgkmcnt(0)
	v_add_f32_e32 v14, v14, v15
	v_mov_b32_e32 v15, v14
	s_nop 1
	v_permlane32_swap_b32_e32 v14, v15
	v_add_f32_e32 v14, v14, v15
	v_fmamk_f32 v14, v14, 0x3c000000, v215
	v_rsq_f32_e32 v14, v14
	s_nop 0
	v_mul_f32_e32 v12, v14, v12
	v_mul_f32_e32 v13, v14, v13
	v_mul_f32_e32 v12, v3, v12
	v_mul_f32_e32 v13, v2, v13
	v_mul_f32_e32 v14, v0, v12
	v_fma_f32 v14, v9, v13, -v14
	v_mul_f32_e32 v12, v9, v12
	v_mul_f32_e32 v14, 0x3e0293ee, v14
	v_fmac_f32_e32 v12, v0, v13
	v_mul_f32_e32 v12, 0x3e0293ee, v12
	v_bfe_u32 v13, v14, 16, 1
	v_add3_u32 v13, v14, v13, s31
	v_bfe_u32 v14, v12, 16, 1
	v_lshrrev_b32_e32 v13, 16, v13
	v_add3_u32 v12, v12, v14, s31
	v_and_or_b32 v12, v12, s71, v13
	flat_store_dword v[6:7], v12 offset:1792
	v_lshlrev_b32_e32 v12, 16, v11
	v_and_b32_e32 v11, 0xffff0000, v11
	v_mul_f32_e32 v13, v11, v11
	v_fmac_f32_e32 v13, v12, v12
	s_nop 1
	v_add_f32_dpp v13, v13, v13 quad_perm:[1,0,3,2] row_mask:0xf bank_mask:0xf
	s_nop 1
	v_add_f32_dpp v13, v13, v13 quad_perm:[2,3,0,1] row_mask:0xf bank_mask:0xf
	s_nop 1
	v_add_f32_dpp v13, v13, v13 row_half_mirror row_mask:0xf bank_mask:0xf
	s_nop 1
	v_add_f32_dpp v13, v13, v13 row_mirror row_mask:0xf bank_mask:0xf
	v_mov_b32_e32 v14, v13
	s_nop 1
	v_permlane16_swap_b32_e32 v13, v14
	s_waitcnt lgkmcnt(0)
	v_add_f32_e32 v13, v13, v14
	v_mov_b32_e32 v14, v13
	s_nop 1
	v_permlane32_swap_b32_e32 v13, v14
	v_add_f32_e32 v13, v13, v14
	v_fmamk_f32 v13, v13, 0x3c000000, v215
	v_rsq_f32_e32 v13, v13
	s_nop 0
	v_mul_f32_e32 v11, v13, v11
	v_mul_f32_e32 v12, v13, v12
	v_mul_f32_e32 v11, v5, v11
	v_mul_f32_e32 v12, v4, v12
	v_mul_f32_e32 v13, v0, v11
	v_fma_f32 v13, v9, v12, -v13
	v_mul_f32_e32 v11, v9, v11
	v_fmac_f32_e32 v11, v0, v12
	v_bfe_u32 v12, v13, 16, 1
	v_add3_u32 v12, v13, v12, s31
	v_bfe_u32 v13, v11, 16, 1
	v_lshrrev_b32_e32 v12, 16, v12
	v_add3_u32 v11, v11, v13, s31
	v_and_or_b32 v11, v11, s71, v12
	flat_store_dword v[6:7], v11 offset:2048
	v_lshlrev_b32_e32 v11, 16, v10
	v_and_b32_e32 v10, 0xffff0000, v10
	v_mul_f32_e32 v12, v10, v10
	v_fmac_f32_e32 v12, v11, v11
	s_nop 1
	v_add_f32_dpp v12, v12, v12 quad_perm:[1,0,3,2] row_mask:0xf bank_mask:0xf
	s_nop 1
	v_add_f32_dpp v12, v12, v12 quad_perm:[2,3,0,1] row_mask:0xf bank_mask:0xf
	s_nop 1
	v_add_f32_dpp v12, v12, v12 row_half_mirror row_mask:0xf bank_mask:0xf
	s_nop 1
	v_add_f32_dpp v12, v12, v12 row_mirror row_mask:0xf bank_mask:0xf
	v_mov_b32_e32 v13, v12
	s_nop 1
	v_permlane16_swap_b32_e32 v12, v13
	s_waitcnt lgkmcnt(0)
	v_add_f32_e32 v12, v12, v13
	v_mov_b32_e32 v13, v12
	s_nop 1
	v_permlane32_swap_b32_e32 v12, v13
	v_add_f32_e32 v12, v12, v13
	v_fmamk_f32 v12, v12, 0x3c000000, v215
	v_rsq_f32_e32 v12, v12
	s_nop 0
	v_mul_f32_e32 v10, v12, v10
	v_mul_f32_e32 v11, v12, v11
	v_mul_f32_e32 v10, v5, v10
	v_mul_f32_e32 v11, v4, v11
	v_mul_f32_e32 v12, v0, v10
	v_fma_f32 v12, v9, v11, -v12
	v_mul_f32_e32 v9, v9, v10
	v_fmac_f32_e32 v9, v0, v11
	v_bfe_u32 v0, v12, 16, 1
	v_add3_u32 v0, v12, v0, s31
	v_bfe_u32 v10, v9, 16, 1
	v_lshrrev_b32_e32 v0, 16, v0
	v_add3_u32 v9, v9, v10, s31
	v_and_or_b32 v0, v9, s71, v0
	flat_store_dword v[6:7], v0 offset:2304
	v_lshl_add_u64 v[6:7], v[6:7], 0, s[0:1]
	s_cbranch_scc1 .LBB0_421

; __device__ __forceinline__ float bf_lo(unsigned w) { return __uint_as_float(w << 16); }
; __device__ __forceinline__ float bf_hi(unsigned w) { return __uint_as_float(w & 0xffff0000u); }
; __device__ __forceinline__ unsigned pk2(float lo, float hi) { return f2bf(lo) | (f2bf(hi) << 16); }
; #define WS_SWZ(x, pat) __int_as_float(__builtin_amdgcn_ds_swizzle(__float_as_int(x), (pat)))
; __device__ __forceinline__ float wave_sum(float v) {
;     ...
;     v += WS_SWZ(v, 0x041F); v += WS_SWZ(v, 0x081F); v += WS_SWZ(v, 0x101F); v += WS_SWZ(v, 0x201F); v += WS_SWZ(v, 0x401F);
;     ...
;     auto rr = __builtin_amdgcn_permlane32_swap(__float_as_uint(v), __float_as_uint(v), false, false);
;     return __uint_as_float(rr[0]) + __uint_as_float(rr[1]);
; }
; __global__ void __launch_bounds__(NWAVES * 64) fwd_kernel(Args args) {
;     ...
;               for (int wt = wave_ * G + (int)blockIdx.x; wt < TROWS * (DM / 8) / 64; wt += G * NWAVES) { const int i = wt * 64 + (ltid_ & 63); const int row = i / (DM / 8), c8 = (i % (DM / 8)) * 8;
;                   f32x4 s0, s1;
;                   if (K == DFF) slab_sum<DFF / KSPLIT>(slab, row, c8, s0, s1); else slab_sum<DM / KSPLIT>(slab, row, c8, s0, s1);
;                   bf16_t* hp = HB + (size_t)(MFULL + row) * DM + c8; const v4u h = *(const v4u*)hp;
;                   const float n0 = pg8::bf_lo(h.x) + alpha * s0.x, n1 = pg8::bf_hi(h.x) + alpha * s0.y, n2 = pg8::bf_lo(h.y) + alpha * s0.z, n3 = pg8::bf_hi(h.y) + alpha * s0.w;
;                   const float n4 = pg8::bf_lo(h.z) + alpha * s1.x, n5 = pg8::bf_hi(h.z) + alpha * s1.y, n6 = pg8::bf_lo(h.w) + alpha * s1.z, n7 = pg8::bf_hi(h.w) + alpha * s1.w;
;                   v4u w; w.x = pk2(n0, n1); w.y = pk2(n2, n3); w.z = pk2(n4, n5); w.w = pk2(n6, n7); *(v4u*)hp = w;
;                   const float sq = wave_sum((n0 * n0 + n1 * n1) + (n2 * n2 + n3 * n3) + (n4 * n4 + n5 * n5) + (n6 * n6 + n7 * n7));
;                   if ((ltid_ & 63) == 0) atomicAdd(ssn + MFULL + row, sq); } }
.LBB0_554:
	v_readlane_b32 s6, v254, 25
	v_lshlrev_b64 v[6:7], 12, v[2:3]
	v_readlane_b32 s7, v254, 26
	v_mov_b32_e32 v21, v12
	v_mov_b32_e32 v12, v15
	v_lshl_add_u64 v[6:7], s[6:7], 0, v[6:7]
	v_lshl_add_u64 v[4:5], v[4:5], 1, v[6:7]
	v_add_co_u32_e32 v16, vcc, 0x6000000, v4
	v_mov_b32_e32 v20, v14
	s_nop 0
	v_addc_co_u32_e32 v17, vcc, 0, v5, vcc
	flat_load_dwordx4 v[4:7], v[16:17]
	v_mov_b32_e32 v14, v10
	v_mov_b32_e32 v15, v8
	v_mov_b32_e32 v8, v11
	s_waitcnt vmcnt(0) lgkmcnt(0)
	v_lshlrev_b32_e32 v19, 16, v5
	v_lshlrev_b32_e32 v18, 16, v4
	v_and_b32_e32 v5, 0xffff0000, v5
	v_and_b32_e32 v4, 0xffff0000, v4
	v_pk_fma_f32 v[12:13], v[158:159], v[12:13], v[4:5]
	v_lshlrev_b32_e32 v5, 16, v7
	v_lshlrev_b32_e32 v4, 16, v6
	v_pk_fma_f32 v[18:19], v[158:159], v[20:21], v[18:19]
	v_pk_fma_f32 v[14:15], v[158:159], v[14:15], v[4:5]
	v_and_b32_e32 v5, 0xffff0000, v7
	v_and_b32_e32 v4, 0xffff0000, v6
	v_bfe_u32 v6, v13, 16, 1
	v_bfe_u32 v7, v12, 16, 1
	v_pk_fma_f32 v[8:9], v[158:159], v[8:9], v[4:5]
	v_add3_u32 v10, v12, v7, s31
	v_add3_u32 v11, v13, v6, s31
	v_bfe_u32 v6, v18, 16, 1
	v_bfe_u32 v7, v19, 16, 1
	v_bfe_u32 v20, v14, 16, 1
	v_bfe_u32 v21, v15, 16, 1
	v_bfe_u32 v4, v9, 16, 1
	v_bfe_u32 v5, v8, 16, 1
	v_add3_u32 v21, v15, v21, s31
	v_add3_u32 v20, v14, v20, s31
	v_add3_u32 v7, v19, v7, s31
	v_add3_u32 v6, v18, v6, s31
	v_add3_u32 v5, v8, v5, s31
	v_add3_u32 v4, v9, v4, s31
	v_lshrrev_b32_e32 v22, 16, v6
	v_lshrrev_b32_e32 v23, 16, v7
	v_lshrrev_b32_e32 v6, 16, v20
	v_lshrrev_b32_e32 v7, 16, v21
	v_and_or_b32 v7, v4, s71, v7
	v_and_or_b32 v6, v5, s71, v6
	v_and_or_b32 v5, v11, s71, v23
	v_and_or_b32 v4, v10, s71, v22
	flat_store_dwordx4 v[16:17], v[4:7]
	s_nop 1
	v_pk_mul_f32 v[4:5], v[12:13], v[12:13]
	v_pk_mul_f32 v[6:7], v[8:9], v[8:9]
	v_pk_fma_f32 v[4:5], v[18:19], v[18:19], v[4:5]
	v_pk_fma_f32 v[6:7], v[14:15], v[14:15], v[6:7]
	v_add_f32_e32 v4, v4, v5
	v_add_f32_e32 v4, v6, v4
	v_add_f32_e32 v4, v7, v4
	s_nop 1
	v_add_f32_dpp v4, v4, v4 quad_perm:[1,0,3,2] row_mask:0xf bank_mask:0xf
	s_nop 1
	v_add_f32_dpp v4, v4, v4 quad_perm:[2,3,0,1] row_mask:0xf bank_mask:0xf
	s_nop 1
	v_add_f32_dpp v4, v4, v4 row_half_mirror row_mask:0xf bank_mask:0xf
	s_nop 1
	v_add_f32_dpp v4, v4, v4 row_mirror row_mask:0xf bank_mask:0xf
	v_mov_b32_e32 v5, v4
	s_nop 1
	v_permlane16_swap_b32_e32 v4, v5
	s_waitcnt lgkmcnt(0)
	v_add_f32_e32 v4, v4, v5
	v_mov_b32_e32 v5, v4
	s_nop 1
	v_permlane32_swap_b32_e32 v4, v5
	s_and_saveexec_b64 s[6:7], s[40:41]
	s_cbranch_execz .LBB0_551
	v_lshl_add_u64 v[2:3], v[2:3], 2, s[0:1]
	v_add_f32_e32 v4, v4, v5
	flat_atomic_add_f32 v[2:3], v4
	s_branch .LBB0_551

; __device__ __forceinline__ unsigned pk2(float lo, float hi) { return f2bf(lo) | (f2bf(hi) << 16); }
; #define WS_SWZ(x, pat) __int_as_float(__builtin_amdgcn_ds_swizzle(__float_as_int(x), (pat)))
; __device__ __forceinline__ float wave_sum(float v) {
;     ...
;     v += WS_SWZ(v, 0x041F); v += WS_SWZ(v, 0x081F); v += WS_SWZ(v, 0x101F); v += WS_SWZ(v, 0x201F); v += WS_SWZ(v, 0x401F);
;     ...
;     auto rr = __builtin_amdgcn_permlane32_swap(__float_as_uint(v), __float_as_uint(v), false, false);
;     return __uint_as_float(rr[0]) + __uint_as_float(rr[1]);
; }
; __global__ void __launch_bounds__(NWAVES * 64) fwd_kernel(Args args) {
;     ...
;             for (int r = gw; r < MPAD; r += NGW) {
;                 unsigned long long* o8 = (unsigned long long*)(HB + (size_t)r * DM) + lane; float s2 = 0.f;
;                 if (r < MREAL) {
;                     const int s = r < 4 * LP ? r / LP : 4, t = r < 4 * LP ? r % LP : r - 4 * LP;
;                     const float* src = t < NMETA ? meta + (size_t)t * DM : (s < 4 ? x_prompt + ((size_t)s * 2048 + (t - NMETA)) * DM : x_sample + (size_t)(t - NMETA) * DM);
;                     const f32x4* xr = (const f32x4*)src + lane;
; #pragma unroll
;                     for (int j = 0; j < 8; ++j) { const f32x4 v = __builtin_nontemporal_load(xr + 64 * j); s2 += (v.x * v.x + v.y * v.y) + (v.z * v.z + v.w * v.w);
;                         o8[64 * j] = (unsigned long long)pk2(v.x, v.y) | ((unsigned long long)pk2(v.z, v.w) << 32); }
;                     s2 = wave_sum(s2);
;                 } else {
; #pragma unroll
;                     for (int j = 0; j < 8; ++j) o8[64 * j] = 0ull;
;                 }
;                 if (lane == 0) ssb[r] = s2;
;             }
.LBB0_648:
	s_lshl_b64 s[10:11], s[14:15], 13
	s_add_u32 s10, s12, s10
	s_addc_u32 s11, s13, s11
	global_load_dwordx4 v[10:13], v0, s[10:11] nt
	v_lshl_add_u64 v[26:27], s[10:11], 0, v[0:1]
	v_readlane_b32 s16, v254, 27
	v_readlane_b32 s17, v254, 28
	s_waitcnt vmcnt(0)
	v_bfe_u32 v3, v10, 16, 1
	v_bfe_u32 v14, v12, 16, 1
	v_bfe_u32 v5, v11, 16, 1
	v_bfe_u32 v15, v13, 16, 1
	v_add3_u32 v3, v10, v3, s31
	v_add3_u32 v14, v12, v14, s31
	v_add3_u32 v5, v11, v5, s31
	v_add3_u32 v15, v13, v15, s31
	v_lshrrev_b32_e32 v3, 16, v3
	v_lshrrev_b32_e32 v16, 16, v14
	v_and_or_b32 v14, v5, s71, v3
	v_and_or_b32 v15, v15, s71, v16
	flat_store_dwordx2 v[8:9], v[14:15]
	global_load_dwordx4 v[14:17], v0, s[10:11] offset:1024 nt
	v_mov_b32_e32 v44, v13
	s_waitcnt vmcnt(0)
	v_bfe_u32 v3, v14, 16, 1
	v_bfe_u32 v18, v16, 16, 1
	v_bfe_u32 v5, v15, 16, 1
	v_bfe_u32 v19, v17, 16, 1
	v_add3_u32 v3, v14, v3, s31
	v_add3_u32 v18, v16, v18, s31
	v_add3_u32 v5, v15, v5, s31
	v_add3_u32 v19, v17, v19, s31
	v_lshrrev_b32_e32 v3, 16, v3
	v_lshrrev_b32_e32 v20, 16, v18
	v_and_or_b32 v18, v5, s71, v3
	v_and_or_b32 v19, v19, s71, v20
	flat_store_dwordx2 v[8:9], v[18:19] offset:512
	global_load_dwordx4 v[18:21], v0, s[10:11] offset:2048 nt
	v_mov_b32_e32 v43, v15
	v_mov_b32_e32 v45, v17
	v_mov_b32_e32 v13, v16
	v_pk_mul_f32 v[16:17], v[44:45], v[44:45]
	s_waitcnt vmcnt(0)
	v_bfe_u32 v3, v18, 16, 1
	v_bfe_u32 v22, v20, 16, 1
	v_bfe_u32 v5, v19, 16, 1
	v_bfe_u32 v23, v21, 16, 1
	v_add3_u32 v3, v18, v3, s31
	v_add3_u32 v22, v20, v22, s31
	v_add3_u32 v5, v19, v5, s31
	v_add3_u32 v23, v21, v23, s31
	v_lshrrev_b32_e32 v3, 16, v3
	v_lshrrev_b32_e32 v24, 16, v22
	v_and_or_b32 v22, v5, s71, v3
	v_and_or_b32 v23, v23, s71, v24
	flat_store_dwordx2 v[8:9], v[22:23] offset:1024
	global_load_dwordx4 v[22:25], v0, s[10:11] offset:3072 nt
	s_movk_i32 s10, 0x1000
	v_add_co_u32_e32 v38, vcc, s10, v26
	v_pk_fma_f32 v[12:13], v[12:13], v[12:13], v[16:17]
	s_nop 0
	v_addc_co_u32_e32 v39, vcc, 0, v27, vcc
	s_waitcnt vmcnt(0)
	v_bfe_u32 v3, v22, 16, 1
	v_bfe_u32 v26, v24, 16, 1
	v_bfe_u32 v5, v23, 16, 1
	v_bfe_u32 v27, v25, 16, 1
	v_add3_u32 v3, v22, v3, s31
	v_add3_u32 v26, v24, v26, s31
	v_add3_u32 v5, v23, v5, s31
	v_add3_u32 v27, v25, v27, s31
	v_lshrrev_b32_e32 v3, 16, v3
	v_lshrrev_b32_e32 v28, 16, v26
	v_and_or_b32 v26, v5, s71, v3
	v_and_or_b32 v27, v27, s71, v28
	flat_store_dwordx2 v[8:9], v[26:27] offset:1536
	global_load_dwordx4 v[26:29], v[38:39], off nt
	s_waitcnt vmcnt(0)
	v_bfe_u32 v3, v26, 16, 1
	v_bfe_u32 v30, v28, 16, 1
	v_bfe_u32 v5, v27, 16, 1
	v_bfe_u32 v31, v29, 16, 1
	v_add3_u32 v3, v26, v3, s31
	v_add3_u32 v30, v28, v30, s31
	v_add3_u32 v5, v27, v5, s31
	v_add3_u32 v31, v29, v31, s31
	v_lshrrev_b32_e32 v3, 16, v3
	v_lshrrev_b32_e32 v32, 16, v30
	v_and_or_b32 v30, v5, s71, v3
	v_and_or_b32 v31, v31, s71, v32
	flat_store_dwordx2 v[8:9], v[30:31] offset:2048
	global_load_dwordx4 v[30:33], v[38:39], off offset:1024 nt
	s_waitcnt vmcnt(0)
	v_bfe_u32 v3, v30, 16, 1
	v_bfe_u32 v34, v32, 16, 1
	v_bfe_u32 v5, v31, 16, 1
	v_bfe_u32 v35, v33, 16, 1
	v_add3_u32 v3, v30, v3, s31
	v_add3_u32 v34, v32, v34, s31
	v_add3_u32 v5, v31, v5, s31
	v_add3_u32 v35, v33, v35, s31
	v_lshrrev_b32_e32 v3, 16, v3
	v_lshrrev_b32_e32 v36, 16, v34
	v_and_or_b32 v34, v5, s71, v3
	v_and_or_b32 v35, v35, s71, v36
	flat_store_dwordx2 v[8:9], v[34:35] offset:2560
	global_load_dwordx4 v[34:37], v[38:39], off offset:2048 nt
	s_waitcnt vmcnt(0)
	v_bfe_u32 v3, v34, 16, 1
	v_bfe_u32 v40, v36, 16, 1
	v_bfe_u32 v5, v35, 16, 1
	v_bfe_u32 v41, v37, 16, 1
	v_add3_u32 v3, v34, v3, s31
	v_add3_u32 v40, v36, v40, s31
	v_add3_u32 v5, v35, v5, s31
	v_add3_u32 v41, v37, v41, s31
	v_lshrrev_b32_e32 v3, 16, v3
	v_lshrrev_b32_e32 v42, 16, v40
	v_and_or_b32 v40, v5, s71, v3
	v_and_or_b32 v41, v41, s71, v42
	flat_store_dwordx2 v[8:9], v[40:41] offset:3072
	global_load_dwordx4 v[38:41], v[38:39], off offset:3072 nt
	v_mov_b32_e32 v42, v11
	v_mov_b32_e32 v11, v14
	v_pk_mul_f32 v[14:15], v[42:43], v[42:43]
	s_nop 0
	v_pk_fma_f32 v[10:11], v[10:11], v[10:11], v[14:15]
	v_pk_mul_f32 v[14:15], v[18:19], v[18:19]
	v_pk_add_f32 v[10:11], v[10:11], v[12:13]
	v_pk_mul_f32 v[12:13], v[20:21], v[20:21]
	v_pk_add_f32 v[10:11], v[10:11], v[10:11] op_sel:[0,1] op_sel_hi:[1,0]
	v_pk_mov_b32 v[16:17], v[14:15], v[12:13] op_sel:[1,0]
	v_mov_b32_e32 v15, v13
	v_pk_add_f32 v[12:13], v[16:17], v[14:15]
	v_mul_f32_e32 v14, v23, v23
	v_mul_f32_e32 v16, v25, v25
	v_pk_add_f32 v[12:13], v[12:13], v[12:13] op_sel:[0,1] op_sel_hi:[1,0]
	v_pk_fma_f32 v[14:15], v[22:23], v[22:23], v[14:15] op_sel_hi:[1,1,0]
	v_pk_fma_f32 v[16:17], v[24:25], v[24:25], v[16:17] op_sel_hi:[1,1,0]
	v_mul_f32_e32 v11, v26, v26
	v_mul_f32_e32 v13, v27, v27
	v_mul_f32_e32 v15, v28, v28
	v_mul_f32_e32 v17, v29, v29
	v_pk_add_f32 v[10:11], v[10:11], v[12:13]
	v_pk_add_f32 v[12:13], v[14:15], v[16:17]
	v_pk_mul_f32 v[14:15], v[30:31], v[30:31]
	v_pk_add_f32 v[10:11], v[10:11], v[12:13]
	v_pk_mul_f32 v[12:13], v[32:33], v[32:33]
	v_pk_add_f32 v[10:11], v[10:11], v[10:11] op_sel:[0,1] op_sel_hi:[1,0]
	v_pk_mov_b32 v[16:17], v[14:15], v[12:13] op_sel:[1,0]
	v_mov_b32_e32 v15, v13
	v_pk_add_f32 v[12:13], v[16:17], v[14:15]
	v_mul_f32_e32 v14, v35, v35
	v_mul_f32_e32 v16, v37, v37
	v_pk_add_f32 v[12:13], v[12:13], v[12:13] op_sel:[0,1] op_sel_hi:[1,0]
	v_pk_fma_f32 v[14:15], v[34:35], v[34:35], v[14:15] op_sel_hi:[1,1,0]
	v_pk_fma_f32 v[16:17], v[36:37], v[36:37], v[16:17] op_sel_hi:[1,1,0]
	s_waitcnt vmcnt(0)
	v_mul_f32_e32 v11, v38, v38
	v_mul_f32_e32 v13, v39, v39
	v_mul_f32_e32 v15, v40, v40
	v_mul_f32_e32 v17, v41, v41
	v_pk_add_f32 v[10:11], v[10:11], v[12:13]
	v_pk_add_f32 v[12:13], v[14:15], v[16:17]
	s_nop 0
	v_pk_add_f32 v[10:11], v[10:11], v[12:13]
	v_bfe_u32 v12, v40, 16, 1
	v_add_f32_e32 v3, v10, v11
	ds_swizzle_b32 v5, v3 offset:swizzle(SWAP,1)
	v_bfe_u32 v10, v38, 16, 1
	v_bfe_u32 v11, v39, 16, 1
	v_bfe_u32 v13, v41, 16, 1
	v_add3_u32 v10, v38, v10, s31
	s_waitcnt lgkmcnt(0)
	v_add_f32_e32 v3, v3, v5
	ds_swizzle_b32 v5, v3 offset:swizzle(SWAP,2)
	v_add3_u32 v12, v40, v12, s31
	v_add3_u32 v11, v39, v11, s31
	v_add3_u32 v13, v41, v13, s31
	v_lshrrev_b32_e32 v10, 16, v10
	s_waitcnt lgkmcnt(0)
	v_add_f32_e32 v3, v3, v5
	ds_swizzle_b32 v5, v3 offset:swizzle(SWAP,4)
	v_lshrrev_b32_e32 v12, 16, v12
	v_and_or_b32 v10, v11, s71, v10
	v_and_or_b32 v11, v13, s71, v12
	flat_store_dwordx2 v[8:9], v[10:11] offset:3584
	s_waitcnt lgkmcnt(0)
	v_add_f32_e32 v3, v3, v5
	s_nop 1
	v_add_f32_dpp v3, v3, v3 row_mirror row_mask:0xf bank_mask:0xf
	v_mov_b32_e32 v5, v3
	s_nop 1
	v_permlane16_swap_b32_e32 v3, v5
	s_waitcnt lgkmcnt(0)
	v_add_f32_e32 v3, v3, v5
	v_mov_b32_e32 v5, v3
	s_nop 1
	v_permlane32_swap_b32_e32 v3, v5
	v_add_f32_e32 v3, v3, v5
	s_and_saveexec_b64 s[10:11], s[40:41]
	s_cbranch_execz .LBB0_631
